# conv Toeplitz image R1 shifted by 68 bytes so even/odd lane reads hit disjoint LDS banks
# speedup vs baseline: 1.0067x; 1.0018x over previous
;     ...
;   const int tid = opaque_tid(wvs), lane = tid & 63, w = tid >> 6, r = lane & 31, hh = lane >> 5;
;   const int wm = w >> 1, wn = w & 1;
;   const int xcd = blockIdx.x & 7, slot = blockIdx.x >> 3;
;   constexpr int mpx = 1 << LMPX, nslots = 32;
;   const int ntx = mpx * Ntiles, nk = K / 64, lnk = (nk == 16) ? 4 : 5;
;   if (slot >= ntx) return;
;   const int nmine = (ntx - slot + nslots - 1) / nslots;
;   const int S = nmine * nk;
;   const bool sq = (Ntiles & 7) == 0;
; extern "C" __global__ void __launch_bounds__(NT) fwd_megakernel(Params p) {
;     ...
;   XcdBarrier xb = xcd_barrier_post((unsigned*)(p.ws + OFF_BAR), bst, wvs);
;   const float alpha = 1.6817928305074290f;
;   bf16_t* HB = (bf16_t*)(p.ws + OFF_HB);
;   bf16_t* WTIN = (bf16_t*)(p.ws + OFF_WTIN);
;   bf16_t* WTOUT = (bf16_t*)(p.ws + OFF_WTOUT);
;   bf16_t* KF = (bf16_t*)(p.ws + OFF_KF);
;   bf16_t* KB = (bf16_t*)(p.ws + OFF_KB);
;   bf16_t* PROJ = (bf16_t*)(p.ws + OFF_PROJ);
;   bf16_t* AUX = (bf16_t*)(p.ws + OFF_AUX);
;   float* hbuf = p.out;
;   const int one = (p.out != nullptr) ? 1 : 0;
;   (void)one;
;   for (int rep = 0; rep < REP_MISC; ++rep) cvt_phase(wvs, p.in[0], HB);
;   for (int rep = 0; rep < REP_MISC; ++rep) wtrans_phase(wvs, smem, p.in[2], 1024, 8192, 2048, 4096, 4096, WTIN);
;   for (int rep = 0; rep < REP_MISC; ++rep) wtrans_phase(wvs, smem, p.in[2], 1024, 8192, 0, 2048, 2048, WTIN + (size_t)4096 * 1024);
;   for (int rep = 0; rep < REP_MISC; ++rep) wtrans_phase(wvs, smem, p.in[2], 1024, 8192, 6144, 2048, 2048, WTIN + (size_t)6144 * 1024);
;   for (int rep = 0; rep < REP_MISC; ++rep) wtrans_phase(wvs, smem, p.in[14], 2048, 1024, 0, 1024, 1024, WTOUT);
;   for (int rep = 0; rep < REP_MISC; ++rep) hy_filter_phase(wvs, smem, p.in[5], p.in[6], p.in[7], p.in[8], p.in[9], p.in[10], p.in[11], p.in[12], p.in[13], KF, KB);
;   grid.sync();
;   for (int layer = 0; layer < 4; ++layer) {
;     if (layer == 0 || layer == 3) {
;       const int pbase = layer == 0 ? 2 : 32;
;       bf16_t* X1T = (bf16_t*)p.out;
;       bf16_t* VT = (bf16_t*)(p.ws + OFF_VT);
;       bf16_t* PROJ2 = (bf16_t*)(p.ws + OFF_PROJ2);
;       bf16_t* YBUF = (bf16_t*)(p.ws + OFF_YBUF);
;       for (int rep = 0; rep < REP_GEMM; ++rep) gemm_phase<2, 4>(wvs, smem, HB, 1024, WTIN, 1024, 128, 16, X1T, 0, nullptr, VT, 0.f, (REP_GEMM == 1) || (rep + one == REP_GEMM));
.LBB0_193:
	s_or_b64 exec, exec, s[0:1]
	s_add_u32 s30, s76, 0x7a00000
	s_addc_u32 s31, s77, 0
	s_add_u32 s94, s76, 0x17a00000
	s_addc_u32 s95, s77, 0
	s_add_u32 s36, s76, 0x11e00000
	s_addc_u32 s37, s77, 0
	s_add_u32 s4, s76, 0x17e00000
	s_addc_u32 s5, s77, 0
	v_writelane_b32 v251, s4, 22
	s_add_u32 s2, s76, 0x1be00000
	s_addc_u32 s3, s77, 0
	v_writelane_b32 v251, s5, 23
	v_writelane_b32 v251, s2, 24
	s_lshr_b32 s33, s68, 3
	s_mul_i32 s0, s23, s22
	v_writelane_b32 v251, s3, 25
	s_cmpk_lt_u32 s68, 0x100
	v_readlane_b32 s8, v251, 0
	v_readlane_b32 s9, v251, 1
	s_load_dword s1, s[8:9], 0x190
	s_mov_b32 s48, s22
	s_barrier
	s_waitcnt lgkmcnt(0)
	s_load_dwordx4 s[44:47], s[8:9], 0xf8
	s_mul_i32 s12, s0, s1
	s_cselect_b64 s[0:1], -1, 0
	v_writelane_b32 v251, s0, 26
	v_mov_b32_e32 v129, 0
	v_mbcnt_lo_u32_b32 v1, -1, 0
	v_writelane_b32 v251, s1, 27
	s_and_b32 s1, s68, 7
	s_lshl_b32 s0, s68, 17
	s_and_b32 s0, s0, 0x700000
	s_lshl_b32 s2, s1, 23
	s_or_b32 s0, s2, s0
	s_add_u32 s2, s4, s0
	s_addc_u32 s3, s5, 0
	v_writelane_b32 v251, s2, 28
	v_mov_b32_e32 v180, 1
	v_mov_b32_e32 v177, 0x3727c5ac
	v_writelane_b32 v251, s3, 29
	s_lshl_b32 s3, s68, 14
	s_lshl_b32 s2, s68, 13
	s_and_b32 s3, s3, 0x300000
	v_readlane_b32 s4, v251, 15
	v_readlane_b32 s5, v251, 16
	s_add_u32 s4, s4, s3
	s_addc_u32 s5, s5, 0
	s_lshl_b32 s3, s68, 5
	s_lshl_b32 s1, s1, 11
	s_and_b32 s3, s3, 0x700
	s_or_b32 s20, s3, s1
	s_lshl_b32 s1, s68, 2
	v_writelane_b32 v251, s4, 30
	s_and_b32 s1, s1, 0x300
	s_lshl_b32 s93, s33, 16
	v_writelane_b32 v251, s5, 31
	s_cmpk_lt_u32 s68, 0x540
	v_writelane_b32 v251, s1, 32
	s_cselect_b64 s[4:5], -1, 0
	s_sub_i32 s1, 0xc7, s33
	v_writelane_b32 v251, s4, 33
	s_lshr_b32 s1, s1, 1
	s_and_b32 s1, s1, 0x1f0
	v_writelane_b32 v251, s5, 34
	v_writelane_b32 v251, s1, 35
	s_add_i32 s1, s1, -1
	v_writelane_b32 v251, s1, 36
	s_lshl_b32 s1, s68, 3
	v_writelane_b32 v251, s1, 37
	s_and_b32 s1, s1, 56
	s_bfe_u32 s3, s68, 0x30003
	s_or_b32 s3, s1, s3
	s_lshl_b32 s4, s3, 8
	s_lshl_b32 s3, s3, 19
	v_writelane_b32 v251, s4, 38
	s_add_u32 s3, s76, s3
	v_writelane_b32 v251, s3, 39
	s_addc_u32 s3, s77, 0
	s_and_b32 s2, s2, 0xf80000
	s_add_u32 s2, s62, s2
	v_writelane_b32 v251, s3, 40
	s_addc_u32 s3, s63, 0
	s_add_u32 s66, s76, 0x1ff00200
	s_addc_u32 s67, s77, 0
	s_add_u32 s64, s76, 0x1ff00400
	s_addc_u32 s65, s77, 0
	s_add_u32 s22, s76, 0x1ff00500
	v_writelane_b32 v251, s2, 41
	s_addc_u32 s23, s77, 0
	v_mov_b32_e32 v210, 0x3c0881c4
	v_writelane_b32 v251, s3, 42
	s_add_u32 s2, s76, 0x1ff00600
	s_addc_u32 s3, s77, 0
	v_writelane_b32 v251, s2, 43
	v_mov_b32_e32 v211, 0xbab64f3b
	v_mov_b32_e32 v212, 0x4000
	v_writelane_b32 v251, s3, 44
	s_add_u32 s2, s76, 0x1ff00700
	s_addc_u32 s3, s77, 0
	v_writelane_b32 v251, s2, 45
	v_mov_b32_e32 v181, 0x7f800000
	v_mbcnt_hi_u32_b32 v178, -1, v1
	v_writelane_b32 v251, s3, 46
	s_add_u32 s2, s76, 0x1ff00800
	s_addc_u32 s3, s77, 0
	v_writelane_b32 v251, s2, 47
	v_not_b32_e32 v213, 63
	v_not_b32_e32 v179, 31
	v_writelane_b32 v251, s3, 48
	s_add_u32 s2, s76, 0x1ff00900
	s_addc_u32 s3, s77, 0
	v_writelane_b32 v251, s2, 49
	v_mov_b32_e32 v214, 0x7fc00000
	v_mov_b32_e32 v186, 0x1800
	v_writelane_b32 v251, s3, 50
	s_add_u32 s2, s76, 0x1ff00a00
	s_addc_u32 s3, s77, 0
	v_writelane_b32 v251, s2, 51
	v_mov_b32_e32 v130, 0x3f317218
	s_movk_i32 s96, 0x90
	v_writelane_b32 v251, s3, 52
	s_add_u32 s2, s76, 0x1ff00b00
	s_addc_u32 s3, s77, 0
	v_writelane_b32 v251, s2, 53
	s_mov_b32 s97, 0x3fb8aa3b
	s_movk_i32 s61, 0x1f8
	v_writelane_b32 v251, s3, 54
	s_add_u32 s2, s76, 0x1ff00c00
	s_addc_u32 s3, s77, 0
	v_writelane_b32 v251, s2, 55
	s_nop 1
	v_writelane_b32 v251, s3, 56
	s_add_u32 s2, s76, 0x1ff00d00
	s_addc_u32 s3, s77, 0
	s_add_u32 s18, s76, 0x1ff00e00
	s_addc_u32 s19, s77, 0
	s_add_u32 s38, s76, 0x1ff00f00
	s_addc_u32 s39, s77, 0
	s_add_u32 s16, s76, 0x1ff01000
	s_addc_u32 s17, s77, 0
	s_add_u32 s26, s76, 0x1ff01100
	s_addc_u32 s27, s77, 0
	s_add_u32 s14, s76, 0x1ff01200
	s_addc_u32 s15, s77, 0
	s_add_u32 s34, s76, 0x1ff01300
	s_addc_u32 s35, s77, 0
	v_writelane_b32 v251, s2, 57
	s_cmp_eq_u32 s40, 15
	s_nop 0
	v_writelane_b32 v251, s3, 58
	s_cselect_b64 s[2:3], -1, 0
	v_writelane_b32 v251, s2, 59
	s_cmp_eq_u32 s40, 14
	s_nop 0
	v_writelane_b32 v251, s3, 60
	s_cselect_b64 s[2:3], -1, 0
	v_writelane_b32 v251, s2, 61
	s_cmp_eq_u32 s40, 13
	s_nop 0
	v_writelane_b32 v251, s3, 62
	s_cselect_b64 s[2:3], -1, 0
	v_writelane_b32 v251, s2, 63
	s_cmp_eq_u32 s40, 12
	s_nop 0
	v_writelane_b32 v252, s3, 0
	s_cselect_b64 s[2:3], -1, 0
	v_writelane_b32 v252, s2, 1
	s_cmp_eq_u32 s40, 11
	s_nop 0
	v_writelane_b32 v252, s3, 2
	s_cselect_b64 s[2:3], -1, 0
	v_writelane_b32 v252, s2, 3
	s_cmp_eq_u32 s40, 10
	s_nop 0
	v_writelane_b32 v252, s3, 4
	s_cselect_b64 s[2:3], -1, 0
	v_writelane_b32 v252, s2, 5
	s_cmp_eq_u32 s40, 9
	s_nop 0
	v_writelane_b32 v252, s3, 6
	s_cselect_b64 s[2:3], -1, 0
	v_writelane_b32 v252, s2, 7
	s_cmp_eq_u32 s40, 8
	s_nop 0
	v_writelane_b32 v252, s3, 8
	s_cselect_b64 s[2:3], -1, 0
	v_writelane_b32 v252, s2, 9
	s_cmp_eq_u32 s40, 7
	s_nop 0
	v_writelane_b32 v252, s3, 10
	s_cselect_b64 s[2:3], -1, 0
	v_writelane_b32 v252, s2, 11
	s_cmp_eq_u32 s40, 6
	s_nop 0
	v_writelane_b32 v252, s3, 12
	s_cselect_b64 s[2:3], -1, 0
	v_writelane_b32 v252, s2, 13
	s_cmp_eq_u32 s40, 5
	s_nop 0
	v_writelane_b32 v252, s3, 14
	s_cselect_b64 s[2:3], -1, 0
	v_writelane_b32 v252, s2, 15
	s_cmp_eq_u32 s40, 4
	s_nop 0
	v_writelane_b32 v252, s3, 16
	s_cselect_b64 s[2:3], -1, 0
	v_writelane_b32 v252, s2, 17
	s_cmp_eq_u32 s40, 3
	s_nop 0
	v_writelane_b32 v252, s3, 18
	s_cselect_b64 s[2:3], -1, 0
	v_writelane_b32 v252, s2, 19
	s_cmp_eq_u32 s40, 2
	s_nop 0
	v_writelane_b32 v252, s3, 20
; __device__ __forceinline__ unsigned xb_ld(unsigned* p)              { return __hip_atomic_load(p, __ATOMIC_RELAXED, __HIP_MEMORY_SCOPE_AGENT); }
; __device__ __forceinline__ void xcd_barrier_complete(unsigned* bar, unsigned x, unsigned& nloc, unsigned& nx) {
;     const unsigned G = gridDim.x * gridDim.y * gridDim.z;
;     unsigned sum, cnt, mine, sp = 0u;
;     for (;;) {
;         sum = 0u; cnt = 0u; mine = 0u;
; #pragma unroll
;         for (unsigned j = 0; j < 16; ++j) { const unsigned c = xb_ld(&bar[XB_XCNT(j)]); sum += c; cnt += (c > 0u) ? 1u : 0u; mine = (j == x) ? c : mine; }
;         if (sum == G) break;
;         __builtin_amdgcn_s_sleep(1);
;         if ((++sp & 255u) == 0u) { if (xb_ld(&bar[XB_TMO])) break; if (sp > XB_SPIN_CAP) { atomicAdd(&bar[XB_TMO], 1u); break; } }
;     }
;     nloc = mine > 0u ? mine : 1u; nx = cnt > 0u ? cnt : 1u;
;     ...
;   const int tid = opaque_tid(wvs), lane = tid & 63, w = tid >> 6, r = lane & 31, hh = lane >> 5;
;   const int wm = w >> 1, wn = w & 1;
;   const int xcd = blockIdx.x & 7, slot = blockIdx.x >> 3;
;   constexpr int mpx = 1 << LMPX, nslots = 32;
;   const int ntx = mpx * Ntiles, nk = K / 64, lnk = (nk == 16) ? 4 : 5;
;   if (slot >= ntx) return;
;   const int nmine = (ntx - slot + nslots - 1) / nslots;
;   const int S = nmine * nk;
;   const bool sq = (Ntiles & 7) == 0;
;     ...
;   const int drr = lane >> 3, dch = (lane & 7) ^ (((w & 1) * 4 + (drr >> 1)) & 7);
;   const int drow = w * 8 + drr, dcol = dch * 8;
;   const unsigned dA = (unsigned)(drow * lda + dcol), dB = (unsigned)(drow * K + dcol);
	s_cselect_b64 s[2:3], -1, 0
	v_writelane_b32 v252, s2, 21
	s_cmp_eq_u32 s40, 1
	s_nop 0
	v_writelane_b32 v252, s3, 22
	s_cselect_b64 s[2:3], -1, 0
	v_writelane_b32 v252, s2, 23
	s_cmp_eq_u32 s40, 0
	s_nop 0
	v_writelane_b32 v252, s3, 24
	s_cselect_b64 s[2:3], -1, 0
	v_writelane_b32 v252, s2, 25
	s_nop 1
	v_writelane_b32 v252, s3, 26
	s_lshl_b32 s2, s40, 8
	s_add_u32 s2, s28, s2
	s_addc_u32 s3, s29, 0
	s_add_u32 s4, s2, 0x1400
	s_addc_u32 s5, s3, 0
	v_writelane_b32 v252, s4, 27
	s_add_u32 s2, s2, 0x2400
	s_addc_u32 s3, s3, 0
	v_writelane_b32 v252, s5, 28
	v_writelane_b32 v252, s2, 29
	s_mov_b32 s29, 0
	s_mov_b32 s21, s29
	v_writelane_b32 v252, s3, 30
	s_add_u32 s2, s76, 0x1ff03400
	s_addc_u32 s3, s77, 0
	v_writelane_b32 v252, s2, 31
	s_nop 1
	v_writelane_b32 v252, s3, 32
	s_add_u32 s2, s76, 0x1ff03500
	s_addc_u32 s3, s77, 0
	v_writelane_b32 v252, s2, 33
	s_cmpk_lt_i32 s68, 0x100
	s_nop 0
	v_writelane_b32 v252, s3, 34
	s_cselect_b64 s[2:3], -1, 0
	s_lshl_b32 s13, s48, 3
	v_writelane_b32 v252, s2, 35
	s_cmpk_lt_i32 s68, 0xa00
	s_nop 0
	v_writelane_b32 v252, s3, 36
	s_cselect_b64 s[2:3], -1, 0
	s_add_u32 s58, s76, 0xfa00000
	s_addc_u32 s59, s77, 0
	v_writelane_b32 v252, s2, 37
	s_cmpk_lt_u32 s68, 0x800
	s_nop 0
	v_writelane_b32 v252, s3, 38
	s_cselect_b64 s[2:3], -1, 0
	v_writelane_b32 v252, s2, 39
	s_lshl_b32 s4, s68, 4
	s_bfe_u32 s5, s68, 0x20003
	v_writelane_b32 v252, s3, 40
	s_sub_i32 s2, 0x11f, s33
	s_lshr_b32 s2, s2, 1
	s_and_b32 s3, s4, 0x70
	s_lshr_b32 s6, s68, 6
	s_and_b32 s60, s2, 0xf0
	s_lshr_b32 s2, s68, 7
	s_or_b32 s10, s3, s5
	s_and_b32 s3, s6, 12
	s_and_b32 s2, s2, 8
	s_bfe_u32 s7, s68, 0x30005
	s_or_b32 s3, s10, s3
	s_or_b32 s2, s2, s7
	s_lshl_b32 s3, s3, 19
	s_lshr_b32 s40, s68, 5
	v_writelane_b32 v252, s10, 41
	s_add_u32 s10, s76, s3
	s_addc_u32 s11, s77, 0
	s_lshl_b32 s2, s2, 19
	v_writelane_b32 v252, s10, 42
	s_add_u32 s2, s62, s2
	s_addc_u32 s3, s63, 0
	v_writelane_b32 v252, s11, 43
	v_writelane_b32 v252, s2, 44
	s_nop 1
	v_writelane_b32 v252, s3, 45
	v_sub_co_u32_e64 v0, s[2:3], s60, 1
	s_xor_b64 s[2:3], s[2:3], -1
	s_nop 0
	v_writelane_b32 v252, s2, 46
	s_nop 1
	v_writelane_b32 v252, s3, 47
	s_lshl_b32 s2, s7, 24
	s_cmpk_lt_i32 s68, 0x800
	v_writelane_b32 v252, s2, 48
	s_cselect_b64 s[2:3], -1, 0
	v_writelane_b32 v252, s2, 49
	s_nop 1
	v_writelane_b32 v252, s3, 50
	s_add_u32 s2, s94, s0
	s_addc_u32 s3, s95, 0
	v_writelane_b32 v252, s2, 51
	s_cmpk_lt_u32 s68, 0x400
	s_nop 0
	v_writelane_b32 v252, s3, 52
	s_cselect_b64 s[2:3], -1, 0
	v_writelane_b32 v252, s2, 53
	s_nop 1
	v_writelane_b32 v252, s3, 54
	s_sub_i32 s2, 0x9f, s33
	s_lshr_b32 s2, s2, 1
	s_and_b32 s10, s2, 0x70
	s_and_b32 s2, s6, 4
	s_or_b32 s2, s2, s5
	s_or_b32 s2, s2, s1
	s_and_b32 s3, s6, 8
	v_writelane_b32 v252, s10, 55
	s_or_b32 s3, s3, s7
	s_lshl_b32 s2, s2, 19
	v_writelane_b32 v252, s2, 56
	s_lshl_b32 s2, s3, 19
	s_add_i32 s3, s10, -1
	s_add_u32 s2, s72, s2
	v_writelane_b32 v252, s3, 57
	s_addc_u32 s3, s73, 0
	v_writelane_b32 v252, s2, 58
	s_or_b32 s1, s1, s5
	v_readlane_b32 s10, v251, 5
	v_writelane_b32 v252, s3, 59
	v_writelane_b32 v252, s1, 60
	s_lshl_b32 s1, s68, 6
	v_writelane_b32 v252, s1, 61
	s_and_b32 s1, s1, 0x7c0
	s_cmpk_lt_u32 s68, 0x2000
	v_writelane_b32 v252, s1, 62
	s_cselect_b64 s[2:3], -1, 0
	v_writelane_b32 v252, s2, 63
	v_readlane_b32 s11, v251, 6
	s_movk_i32 s5, 0x1800
	v_writelane_b32 v253, s3, 0
	s_lshr_b32 s2, s48, 5
	s_cmp_lg_u64 s[10:11], 0
	s_cselect_b64 s[42:43], -1, 0
	v_writelane_b32 v253, s42, 1
	s_cmpk_lt_i32 s68, 0x540
	s_nop 0
	v_writelane_b32 v253, s43, 2
	s_cselect_b64 s[42:43], -1, 0
	v_writelane_b32 v253, s42, 3
	s_nop 1
	v_writelane_b32 v253, s43, 4
	s_add_u32 s42, s76, 0x1ba00000
	s_addc_u32 s43, s77, 0
	v_writelane_b32 v253, s42, 5
	s_cmpk_lt_u32 s68, 0xa00
	s_nop 0
	v_writelane_b32 v253, s43, 6
	s_cselect_b64 s[42:43], -1, 0
	s_sub_i32 s1, 0x15f, s33
	s_lshr_b32 s1, s1, 1
	v_writelane_b32 v253, s42, 7
	s_and_b32 s3, s1, 0x1f0
	s_and_b32 s1, s6, 56
	v_writelane_b32 v253, s43, 8
	s_or_b32 s1, s1, s7
	v_writelane_b32 v253, s3, 9
	s_lshl_b32 s1, s1, 19
	s_add_i32 s3, s3, -1
	s_add_u32 s42, s62, s1
	v_writelane_b32 v253, s3, 10
	s_addc_u32 s43, s63, 0
	v_writelane_b32 v253, s42, 11
	s_nop 1
	v_writelane_b32 v253, s43, 12
	s_waitcnt lgkmcnt(0)
; DI void hy_conv_phase(int wvs, char* smem, bf16_t* X1T, const bf16_t* __restrict__ VT, const float* __restrict__ cw, const float* __restrict__ cb,
;                       const bf16_t* __restrict__ KF, const bf16_t* __restrict__ KB, bool dostore = true) {
;   bf16_t* Uimg = (bf16_t*)smem;
;   bf16_t* R0 = Uimg + 512 * 72;
;   bf16_t* R1 = R0 + 8192;
;   const int tid = opaque_tid(wvs), lane = tid & 63, w = tid >> 6, n = lane & 31, hh = lane >> 5;
;   for (int c = blockIdx.x; c < 2048; c += gridDim.x) {
;     const float xa = cw[2048 + c], xb = cw[6144 + 2048 + c], xc = cw[12288 + 2048 + c], xbias = cb[2048 + c];
;     const float va = cw[4096 + c], vb = cw[6144 + 4096 + c], vc = cw[12288 + 4096 + c], vbias = cb[4096 + c];
;     const bf16_t* xrow = X1T + (size_t)c * 8 * SEQ;
;     const bf16_t* vrow = VT + (size_t)c * 8 * SEQ;
;     __syncthreads();
; #pragma unroll 2
;     for (int i = 0; i < 8; ++i) {
;       const int e = tid + NT * i, b = e >> 9, t8 = (e & 511) * 8;
;       const bf16_t* xp_ = xrow + b * SEQ + t8;
;       const bf16_t* vp_ = vrow + b * SEQ + t8;
;       const u32x4 xv = *(const u32x4*)xp_, vv = *(const u32x4*)vp_;
;       float fx[10], fv[10];
;       fx[0] = t8 > 0 ? bf2f(xp_[-1]) : 0.f; fv[0] = t8 > 0 ? bf2f(vp_[-1]) : 0.f;
;       fx[9] = t8 + 8 < SEQ ? bf2f(xp_[8]) : 0.f; fv[9] = t8 + 8 < SEQ ? bf2f(vp_[8]) : 0.f;
;       unpack8(xv, fx + 1); unpack8(vv, fv + 1);
;       float u[8];
; #pragma unroll
; extern "C" __global__ void __launch_bounds__(NT) fwd_megakernel(Params p) {
;   extern __shared__ __attribute__((aligned(16))) char smem[];
;   cg::grid_group grid = cg::this_grid();
;   const int wvs = __builtin_amdgcn_readfirstlane((int)(threadIdx.x >> 6));
;   volatile LAS unsigned* bst = (volatile LAS unsigned*)(smem + LDS_BYTES - 16);
;   if (xb_is_t0(wvs)) { bst[0] = 0u; bst[1] = 0u; }
;   __syncthreads();
;   XcdBarrier xb = xcd_barrier_post((unsigned*)(p.ws + OFF_BAR), bst, wvs);
;   const float alpha = 1.6817928305074290f;
;   bf16_t* HB = (bf16_t*)(p.ws + OFF_HB);
;   bf16_t* WTIN = (bf16_t*)(p.ws + OFF_WTIN);
;   bf16_t* WTOUT = (bf16_t*)(p.ws + OFF_WTOUT);
;   bf16_t* KF = (bf16_t*)(p.ws + OFF_KF);
;   bf16_t* KB = (bf16_t*)(p.ws + OFF_KB);
;   bf16_t* PROJ = (bf16_t*)(p.ws + OFF_PROJ);
;   bf16_t* AUX = (bf16_t*)(p.ws + OFF_AUX);
;   float* hbuf = p.out;
;   const int one = (p.out != nullptr) ? 1 : 0;
	s_add_u32 s42, s46, 0x2000
	s_addc_u32 s43, s47, 0
	v_writelane_b32 v253, s42, 13
	s_nop 1
	v_writelane_b32 v253, s43, 14
	s_add_u32 s42, s46, 0x6000
	v_writelane_b32 v253, s44, 15
	s_addc_u32 s43, s47, 0
	s_add_u32 s0, s76, s0
	v_writelane_b32 v253, s45, 16
	v_writelane_b32 v253, s46, 17
	v_writelane_b32 v253, s47, 18
	v_writelane_b32 v253, s42, 19
	s_addc_u32 s1, s77, 0
	s_nop 0
	v_writelane_b32 v253, s43, 20
	v_writelane_b32 v253, s0, 21
	s_nop 1
	v_writelane_b32 v253, s1, 22
	s_add_i32 s0, s4, 17
	v_writelane_b32 v253, s0, 23
	s_lshl_b32 s0, s48, 4
	v_writelane_b32 v253, s0, 24
	s_lshl_b64 s[0:1], s[68:69], 11
	s_add_u32 s0, s76, s0
	s_addc_u32 s1, s77, s1
	s_add_u32 s0, s0, 0x5a00000
	s_addc_u32 s1, s1, 0
	v_writelane_b32 v253, s0, 25
	s_nop 1
	v_writelane_b32 v253, s1, 26
	v_writelane_b32 v253, s20, 27
	s_lshl_b64 s[0:1], s[74:75], 11
	s_mov_b32 s74, s7
	v_writelane_b32 v253, s21, 28
	v_writelane_b32 v253, s0, 29
	s_mov_b32 s20, 0xc2ce8ed0
	s_mov_b32 s21, 0x42b17218
	v_writelane_b32 v253, s1, 30
	s_mov_b32 s0, s68
	v_writelane_b32 v253, s0, 31
	s_mov_b32 s75, 0x800000
	s_nop 0
	v_writelane_b32 v253, s1, 32
	s_lshl_b32 s0, s68, 12
	v_writelane_b32 v253, s0, 33
	s_lshl_b32 s0, s48, 12
	v_writelane_b32 v253, s0, 34
	v_writelane_b32 v253, s40, 35
	s_lshl_b32 s0, s40, 6
	v_writelane_b32 v253, s0, 36
	s_load_dwordx16 s[40:55], s[8:9], 0x118
	v_writelane_b32 v253, s2, 37
	s_lshl_b32 s0, s2, 6
	v_writelane_b32 v253, s0, 38
	v_writelane_b32 v253, s76, 39
	s_waitcnt lgkmcnt(0)
	s_add_u32 s2, s40, 0x200
	v_readfirstlane_b32 s0, v0
	v_writelane_b32 v253, s77, 40
	v_writelane_b32 v253, s40, 41
	s_addc_u32 s3, s41, 0
	s_add_i32 s4, 0, 0x2900
	v_writelane_b32 v253, s41, 42
	v_writelane_b32 v253, s42, 43
	v_writelane_b32 v253, s43, 44
	v_writelane_b32 v253, s44, 45
	v_writelane_b32 v253, s45, 46
	v_writelane_b32 v253, s46, 47
	v_writelane_b32 v253, s47, 48
	v_writelane_b32 v253, s48, 49
	v_writelane_b32 v253, s49, 50
	v_writelane_b32 v253, s50, 51
	v_writelane_b32 v253, s51, 52
	v_writelane_b32 v253, s52, 53
	v_writelane_b32 v253, s53, 54
	v_writelane_b32 v253, s54, 55
	v_writelane_b32 v253, s55, 56
	v_writelane_b32 v253, s2, 57
	s_add_i32 s6, 0, 0x22000
	s_mov_b64 s[68:69], s[22:23]
	v_writelane_b32 v253, s3, 58
	v_writelane_b32 v253, s0, 59
	s_add_i32 s0, 0, 0x277f0
	v_writelane_b32 v253, s0, 60
	s_add_i32 s0, 0, 0x277f4
	v_writelane_b32 v253, s0, 61
	s_add_i32 s0, 0, 0x17c00
	v_writelane_b32 v253, s0, 62
	s_add_i32 s0, 0, 0x11400
	v_writelane_b32 v253, s0, 63
	s_add_i32 s0, 0, 0x18c00
	v_writelane_b32 v254, s0, 0
	s_add_i32 s0, 0, 0x13800
	v_writelane_b32 v254, s0, 1
	v_writelane_b32 v254, s4, 2
	s_add_i32 s4, 0, 0x2100
	v_writelane_b32 v254, s4, 3
	s_add_i32 s4, 0, 0x6900
	v_writelane_b32 v254, s4, 4
	s_add_i32 s4, 0, 0x6100
	v_writelane_b32 v254, s4, 5
	v_writelane_b32 v254, s6, 6
	s_add_i32 s6, 0, 0x11000
	v_writelane_b32 v254, s6, 7
	s_add_i32 s6, 0, 0x19800
	v_writelane_b32 v254, s6, 8
	s_add_i32 s6, 0, 0x1dc00
	v_writelane_b32 v254, s6, 9
	s_add_i32 s6, 0, 0x16042
	v_writelane_b32 v254, s6, 10
	s_add_i32 s6, 0, 0x12000
	s_load_dwordx2 s[22:23], s[8:9], 0x8
	v_writelane_b32 v254, s6, 11
	s_add_i32 s6, 0, 0x16044
	v_writelane_b32 v254, s6, 12
	s_add_i32 s6, 0, 0x1a040
	s_load_dwordx8 s[40:47], s[8:9], 0x158
	v_writelane_b32 v254, s6, 13
	s_mov_b32 s6, 0
	v_writelane_b32 v254, s6, 14
	s_waitcnt lgkmcnt(0)
	v_writelane_b32 v254, s22, 15
	s_load_dwordx16 s[76:91], s[8:9], 0x78
	s_movk_i32 s0, 0xeff
	v_writelane_b32 v254, s23, 16
	v_writelane_b32 v254, s40, 17
	s_movk_i32 s1, 0x1000
	s_movk_i32 s2, 0x3000
	v_writelane_b32 v254, s41, 18
	v_writelane_b32 v254, s42, 19
	v_writelane_b32 v254, s43, 20
	v_writelane_b32 v254, s44, 21
	v_writelane_b32 v254, s45, 22
	v_writelane_b32 v254, s46, 23
	v_writelane_b32 v254, s47, 24
	s_waitcnt lgkmcnt(0)
	v_writelane_b32 v254, s76, 25
	s_mov_b32 s3, 0x5040100
	s_mov_b32 s4, 0xc57ff000
	v_writelane_b32 v254, s77, 26
	v_writelane_b32 v254, s78, 27
	v_writelane_b32 v254, s79, 28
	v_writelane_b32 v254, s80, 29
	v_writelane_b32 v254, s81, 30
	v_writelane_b32 v254, s82, 31
	v_writelane_b32 v254, s83, 32
	v_writelane_b32 v254, s84, 33
	v_writelane_b32 v254, s85, 34
	v_writelane_b32 v254, s86, 35
	v_writelane_b32 v254, s87, 36
	v_writelane_b32 v254, s88, 37
	v_writelane_b32 v254, s89, 38
	v_writelane_b32 v254, s90, 39
	v_writelane_b32 v254, s91, 40
	s_load_dwordx16 s[76:91], s[8:9], 0xb8
	s_waitcnt lgkmcnt(0)
	v_writelane_b32 v254, s76, 41
	s_nop 1
	v_writelane_b32 v254, s77, 42
	v_writelane_b32 v254, s78, 43
	v_writelane_b32 v254, s79, 44
	v_writelane_b32 v254, s80, 45
	v_writelane_b32 v254, s81, 46
	v_writelane_b32 v254, s82, 47
	v_writelane_b32 v254, s83, 48
	v_writelane_b32 v254, s84, 49
	v_writelane_b32 v254, s85, 50
	v_writelane_b32 v254, s86, 51
	v_writelane_b32 v254, s87, 52
	v_writelane_b32 v254, s88, 53
	v_writelane_b32 v254, s89, 54
	v_writelane_b32 v254, s90, 55
	v_writelane_b32 v254, s91, 56
	v_writelane_b32 v254, s24, 57
	s_nop 1
	v_writelane_b32 v254, s25, 58
	v_writelane_b32 v254, s62, 59
	s_nop 1
	v_writelane_b32 v254, s63, 60
	v_writelane_b32 v254, s72, 61
	s_nop 1
	v_writelane_b32 v254, s73, 62
	v_writelane_b32 v254, s70, 63
	s_nop 1
	v_writelane_b32 v255, s71, 0
	v_writelane_b32 v255, s12, 1
	v_writelane_b32 v255, s66, 2
	s_nop 1
	v_writelane_b32 v255, s67, 3
	v_writelane_b32 v255, s64, 4
	s_nop 1
	v_writelane_b32 v255, s65, 5
	v_writelane_b32 v255, s68, 6
	s_nop 1
	v_writelane_b32 v255, s69, 7
	v_writelane_b32 v255, s13, 8
	v_writelane_b32 v255, s60, 9
	v_writelane_b32 v255, s74, 10
	v_writelane_b32 v255, s93, 11
	v_writelane_b32 v255, s58, 12
	s_nop 1
	v_writelane_b32 v255, s59, 13
	s_branch .LBB0_195
